# v63 + hazard s_nop counts on the RWKV critical path trimmed to the required wait states (XF write 10->8, state-update scaling 10->8 / 13->8)
# speedup vs baseline: 1.0025x; 1.0025x over previous
; #define LAS __attribute__((address_space(3)))
; __device__ __forceinline__ f32x4 mfma16(bf16x8 a, bf16x8 b, f32x4 c) { return __builtin_amdgcn_mfma_f32_16x16x32_bf16(a, b, c, 0, 0, 0); }
; __device__ __forceinline__ void rwkv_chunk_item(const P& p, const Ctx& c, int seg, int w, bool save) {
;     ...
;         if (c.wv >= 4) {
;             f32x4 Xt = (f32x4){0.f, 0.f, 0.f, 0.f};
; #pragma unroll
;             for (int kk = 0; kk < 2; ++kk) { const bf16x8 a = *(const LAS bf16x8*)(S0I + (mtq * 16 + l15) * 72 + kk * 32 + quad * 8);
;                 Xt = mfma16(a, *(const LAS bf16x8*)(EA + l15 * 72 + kk * 32 + quad * 8), Xt); Zt = mfma16(a, *(const LAS bf16x8*)(EA + (16 + l15) * 72 + kk * 32 + quad * 8), Zt); }
;             Xt = mfma16(*(const LAS bf16x8*)(UV + (mtq * 16 + l15) * 40 + quad * 8), *(const LAS bf16x8*)(MT1 + l15 * 40 + quad * 8), Xt);
; #pragma unroll
;             for (int jj = 0; jj < 4; ++jj) XF[(mtq * 16 + quad * 4 + jj) * 17 + l15] = Xt[jj];
;         }
.LBB0_888:
	s_and_b32 s87, s86, 1
	s_mul_i32 s2, s87, 0x5c00
	s_add_i32 s88, s2, 0
	v_add_u32_e32 v45, s35, v82
	v_lshlrev_b32_e32 v85, 4, v83
	v_mul_lo_u32 v84, v82, s64
	v_mov_b32_e32 v22, 0
	s_andn2_b64 vcc, exec, s[56:57]
	v_mul_lo_u32 v87, v45, s64
	v_add3_u32 v86, s88, v84, v85
	v_mov_b32_e32 v23, 0
	v_mov_b32_e32 v24, 0
	v_mov_b32_e32 v25, 0
	s_cbranch_vccnz .LBB0_890
	v_mul_lo_u32 v22, v45, s63
	v_add3_u32 v45, 0, v22, v85
	v_mul_lo_u32 v22, v82, s63
	v_add3_u32 v54, s88, v22, v85
	v_add3_u32 v129, s88, v87, v85
	ds_read_b128 v[22:25], v45 offset:47104
	ds_read_b128 v[46:49], v54
	ds_read_b128 v[88:91], v45 offset:47168
	ds_read_b128 v[92:95], v54 offset:64
	ds_read_b128 v[96:99], v129 offset:14336
	ds_read_b128 v[100:103], v86 offset:19456
	ds_read_b128 v[50:53], v54 offset:2304
	ds_read_b128 v[124:127], v54 offset:2368
	s_movk_i32 s2, 0x44
	v_lshl_add_u32 v45, v83, 2, s35
	v_lshlrev_b32_e32 v54, 2, v82
	v_mul_lo_u32 v45, v45, s2
	v_add3_u32 v45, 0, v54, v45
	v_add_u32_e32 v45, 0xdc00, v45
	s_waitcnt lgkmcnt(6)
	v_mfma_f32_16x16x32_bf16 v[46:49], v[22:25], v[46:49], 0
	s_waitcnt lgkmcnt(4)
	v_mfma_f32_16x16x32_bf16 v[46:49], v[88:91], v[92:95], v[46:49]
	s_waitcnt lgkmcnt(2)
	v_mfma_f32_16x16x32_bf16 v[46:49], v[96:99], v[100:103], v[46:49]
	s_nop 7
	ds_write2_b32 v45, v46, v47 offset1:17
	ds_write2_b32 v45, v48, v49 offset0:34 offset1:51
	s_waitcnt lgkmcnt(2)
	v_mfma_f32_16x16x32_bf16 v[22:25], v[22:25], v[50:53], 0
	v_mfma_f32_16x16x32_bf16 v[22:25], v[88:91], v[124:127], v[22:25]

; #define LAS __attribute__((address_space(3)))
; __device__ __forceinline__ bf16_t f2bf(float f) { const __bf16 r = (__bf16)f; bf16_t u; __builtin_memcpy(&u, &r, 2); return u; }
; __device__ __forceinline__ f32x4 mfma16(bf16x8 a, bf16x8 b, f32x4 c) { return __builtin_amdgcn_mfma_f32_16x16x32_bf16(a, b, c, 0, 0, 0); }
; __device__ __forceinline__ void rwkv_chunk_item(const P& p, const Ctx& c, int seg, int w, bool save) {
;     ...
;     auto gtile = [&](int pb, int l15, int quad) {
;         LAS bf16_t* EA = (LAS bf16_t*)(OB + pb * OPB + O_EA); LAS bf16_t* EB = (LAS bf16_t*)(OB + pb * OPB + O_EB);
;         LAS bf16_t* MT1 = (LAS bf16_t*)(OB + pb * OPB + O_MT1); LAS bf16_t* NT = (LAS bf16_t*)(OB + pb * OPB + O_NT); LAS float* MABT = (LAS float*)(OB + pb * OPB + O_MABT);
;         const int sb = c.wv >> 1, tb = c.wv & 1; f32x4 g = (f32x4){0.f, 0.f, 0.f, 0.f};
; #pragma unroll
;         for (int kk = 0; kk < 2; ++kk) g = mfma16(*(const LAS bf16x8*)(EB + (sb * 16 + l15) * 72 + kk * 32 + quad * 8), *(const LAS bf16x8*)(EA + (tb * 16 + l15) * 72 + kk * 32 + quad * 8), g);
; #pragma unroll
;         for (int jj = 0; jj < 4; ++jj) { const int s2 = quad * 4 + jj, tt = l15; const float v = g[jj];
;             if (tb == 0) { const float m = (s2 < tt) ? v : 0.f; if (sb == 0) { MABT[s2 * 20 + tt] = m; MT1[tt * 40 + s2] = 0; } else MT1[tt * 40 + 16 + s2] = f2bf(m); }
;             else { const float m = (s2 <= tt) ? v : 0.f; NT[tt * 40 + sb * 16 + s2] = f2bf(m); } } };
;     ...
; #pragma unroll
;         for (int x = 0; x < 2; ++x) { const int ti = c.wv * 2 + x, mt = ti >> 2, nt = ti & 3;
;             S[x] = mfma16(*(const LAS bf16x8*)(UV + (mt * 16 + l15) * 40 + quad * 8), *(const LAS bf16x8*)(EBT + (nt * 16 + l15) * 40 + quad * 8), S[x]);
;             const float gt = GT[nt * 16 + l15];
; #pragma unroll
;             for (int jj = 0; jj < 4; ++jj) S[x][jj] *= gt; }
;         simg(l15, quad);
;         if (c.wv < 4 && ch + 1 < SEGT / 16) gtile(pb ^ 1, l15, quad);
.LBB0_900:
	s_waitcnt lgkmcnt(2)
	v_mfma_f32_16x16x32_bf16 v[6:9], v[130:133], v[148:151], v[6:9]
	s_waitcnt lgkmcnt(0)
	v_mfma_f32_16x16x32_bf16 v[10:13], v[130:133], v[124:127], v[10:13]
	v_mov_b32_e32 v2, v153
	v_lshlrev_b32_e32 v38, 2, v83
	s_nop 4
	v_pk_mul_f32 v[6:7], v[152:153], v[6:7] op_sel_hi:[0,1]
	v_pk_mul_f32 v[10:11], v[2:3], v[10:11] op_sel_hi:[0,1]
	v_pk_mul_f32 v[12:13], v[2:3], v[12:13] op_sel_hi:[0,1]
	v_add_u32_e32 v2, s45, v38
	v_lshlrev_b32_e32 v22, 1, v82
	v_mul_lo_u32 v2, v2, s63
	v_pk_mul_f32 v[8:9], v[152:153], v[8:9] op_sel_hi:[0,1]
	v_add3_u32 v2, s40, v22, v2
	v_and_b32_e32 v140, 1, v82
	v_cmp_ne_u32_e64 s[2:3], 0, v140
	v_mov_b32_e32 v141, 0x5040100
	v_mov_b32_e32 v142, 0x3020706
	v_mul_u32_u24_e32 v140, 0x11e, v140
	v_cndmask_b32_e64 v141, v141, v142, s[2:3]
	v_add_u32_e32 v140, v2, v140
	v_cvt_pk_bf16_f32 v22, v6, v8
	v_cvt_pk_bf16_f32 v23, v7, v9
	v_cvt_pk_bf16_f32 v142, v10, v12
	v_cvt_pk_bf16_f32 v143, v11, v13
	v_mov_b32_dpp v144, v22 quad_perm:[1,0,3,2] row_mask:0xf bank_mask:0xf bound_ctrl:1
	v_mov_b32_dpp v145, v23 quad_perm:[1,0,3,2] row_mask:0xf bank_mask:0xf bound_ctrl:1
	v_mov_b32_dpp v146, v142 quad_perm:[1,0,3,2] row_mask:0xf bank_mask:0xf bound_ctrl:1
	v_mov_b32_dpp v147, v143 quad_perm:[1,0,3,2] row_mask:0xf bank_mask:0xf bound_ctrl:1
	v_perm_b32 v22, v144, v22, v141
	v_perm_b32 v23, v145, v23, v141
	v_perm_b32 v142, v146, v142, v141
	v_perm_b32 v143, v147, v143, v141
	s_or_b64 s[2:3], s[56:57], s[4:5]
	ds_write_b32 v140, v22 offset:47104
	ds_write_b32 v140, v23 offset:47248
	ds_write_b32 v140, v142 offset:47136
	s_and_b64 vcc, exec, s[2:3]
	ds_write_b32 v140, v143 offset:47280
	s_cbranch_vccnz .LBB0_929
	s_xor_b32 s2, s87, 1
	s_mulk_i32 s2, 0x5c00
	v_add_u32_e32 v2, s67, v82
	s_add_i32 s4, s2, 0
	v_mul_lo_u32 v2, v2, s63
	v_lshlrev_b32_e32 v22, 1, v45
	v_add_u32_e32 v23, s83, v82
	v_add3_u32 v2, s4, v2, v22
	v_mul_lo_u32 v23, v23, s63
	v_add3_u32 v39, s4, v23, v22
	ds_read_b128 v[22:25], v2 offset:4608
	ds_read_b128 v[40:43], v39
	ds_read_b128 v[124:127], v2 offset:4672
	ds_read_b128 v[86:89], v39 offset:64
	s_waitcnt lgkmcnt(2)
	v_mfma_f32_16x16x32_bf16 v[22:25], v[22:25], v[40:43], 0
	v_add_u32_e32 v39, s4, v84
	v_add_u32_e32 v2, s84, v39
	s_waitcnt lgkmcnt(0)
	v_mfma_f32_16x16x32_bf16 v[22:25], v[124:127], v[86:89], v[22:25]
	v_lshl_add_u32 v40, v38, 1, v2
	v_lshl_add_u32 v41, v38, 1, v39
	v_lshl_add_u32 v2, v82, 2, s4
	v_or_b32_e32 v42, 1, v38
	v_or_b32_e32 v43, 2, v38
	v_or_b32_e32 v140, 3, v38
	s_and_b64 vcc, exec, s[72:73]
	s_nop 3
	s_cbranch_vccz .Lrw_mb_notA
	v_cmp_le_i32_e32 vcc, v38, v82
	s_nop 1
	v_cndmask_b32_e32 v22, 0, v22, vcc
	v_cmp_le_i32_e32 vcc, v42, v82
	s_nop 1
	v_cndmask_b32_e32 v23, 0, v23, vcc
	v_cmp_le_i32_e32 vcc, v43, v82
	s_nop 1
	v_cndmask_b32_e32 v24, 0, v24, vcc
	v_cmp_le_i32_e32 vcc, v140, v82
	s_nop 1
	v_cndmask_b32_e32 v25, 0, v25, vcc
	v_cvt_pk_bf16_f32 v22, v22, v23
	v_cvt_pk_bf16_f32 v24, v24, v25
	ds_write_b32 v40, v22 offset:20736
	ds_write_b32 v40, v24 offset:20740
	s_branch .LBB0_929
